# FoX hot loop: 16 packed v_pk_add_f32 between MFMAs split into scalar v_add_f32 pairs (strategy 7.5)
# speedup vs baseline: 1.1252x; 1.0004x over previous
.LBB0_1056:
	s_mul_i32 s30, s37, 0x2400
	v_add_u32_e32 v80, s30, v184
	ds_read_b128 v[76:79], v80
	ds_read_b128 v[92:95], v80 offset:64
	s_lshl_b32 s30, s37, 8
	v_lshl_or_b32 v123, v159, 2, s30
	s_waitcnt lgkmcnt(1)
	v_mfma_f32_16x16x32_bf16 v[96:99], v[76:79], v[4:7], 0
	v_mfma_f32_16x16x32_bf16 v[100:103], v[76:79], v[12:15], 0
	ds_read_b128 v[76:79], v80 offset:2304
	ds_read_b128 v[206:209], v80 offset:2368
	ds_read_b128 v[214:217], v80 offset:4608
	ds_read_b128 v[218:221], v80 offset:4672
	ds_read_b128 v[222:225], v80 offset:6912
	ds_read_b128 v[226:229], v80 offset:6976
	s_waitcnt lgkmcnt(5)
	v_mfma_f32_16x16x32_bf16 v[104:107], v[76:79], v[4:7], 0
	v_mfma_f32_16x16x32_bf16 v[210:213], v[76:79], v[12:15], 0
	s_waitcnt lgkmcnt(3)
	v_mfma_f32_16x16x32_bf16 v[76:79], v[214:217], v[4:7], 0
	v_mfma_f32_16x16x32_bf16 v[96:99], v[92:95], v[8:11], v[96:99]
	v_mfma_f32_16x16x32_bf16 v[104:107], v[206:209], v[8:11], v[104:107]
	s_waitcnt lgkmcnt(1)
	v_mfma_f32_16x16x32_bf16 v[108:111], v[222:225], v[4:7], 0
	v_mfma_f32_16x16x32_bf16 v[144:147], v[218:221], v[8:11], v[76:79]
	ds_read_b128 v[88:91], v123 offset:55296
	ds_read_b128 v[84:87], v123 offset:55360
	ds_read_b128 v[80:83], v123 offset:55424
	ds_read_b128 v[76:79], v123 offset:55488
	s_waitcnt lgkmcnt(3)
	v_add_f32_e32 v152, v96, v88
	v_add_f32_e32 v153, v97, v89
	s_waitcnt lgkmcnt(2)
	v_add_f32_e32 v148, v104, v84
	v_add_f32_e32 v149, v105, v85
	v_add_f32_e32 v150, v98, v90
	v_add_f32_e32 v151, v99, v91
	v_max3_f32 v104, v152, s94, v153
	v_mfma_f32_16x16x32_bf16 v[108:111], v[226:229], v[8:11], v[108:111]
	v_max3_f32 v104, v104, v150, v151
	s_waitcnt lgkmcnt(1)
	v_add_f32_e32 v142, v146, v82
	v_add_f32_e32 v143, v147, v83
	v_add_f32_e32 v146, v106, v86
	v_add_f32_e32 v147, v107, v87
	v_max3_f32 v104, v104, v148, v149
	v_add_f32_e32 v144, v144, v80
	v_add_f32_e32 v145, v145, v81
	v_max3_f32 v104, v104, v146, v147
	v_max3_f32 v104, v104, v144, v145
	s_waitcnt lgkmcnt(0)
	v_add_f32_e32 v140, v108, v76
	v_add_f32_e32 v141, v109, v77
	v_max3_f32 v104, v104, v142, v143
	v_add_f32_e32 v110, v110, v78
	v_add_f32_e32 v111, v111, v79
	v_max3_f32 v108, v104, v140, v141
	v_mfma_f32_16x16x32_bf16 v[104:107], v[92:95], v[16:19], v[100:103]
	v_max3_f32 v92, v108, v110, v111
	v_mov_b32_e32 v93, v92
	s_nop 1
	v_permlane16_swap_b32 v93, v92
	s_waitcnt lgkmcnt(0)
	v_max_f32_e32 v92, v92, v93
	v_mov_b32_e32 v93, v92
	s_nop 1
	v_permlane32_swap_b32 v93, v92
	v_mfma_f32_16x16x32_bf16 v[96:99], v[214:217], v[12:15], 0
	s_waitcnt lgkmcnt(0)
	v_max3_f32 v108, v2, v92, v93
	v_mfma_f32_16x16x32_bf16 v[214:217], v[222:225], v[12:15], 0
	v_cmp_neq_f32_e32 vcc, s94, v108
	v_mfma_f32_16x16x32_bf16 v[100:103], v[206:209], v[16:19], v[210:213]
	s_nop 0
	v_cndmask_b32_e32 v123, 0, v108, vcc
	v_cmp_gt_f32_e32 vcc, v108, v2
	v_mfma_f32_16x16x32_bf16 v[96:99], v[218:221], v[16:19], v[96:99]
	v_mfma_f32_16x16x32_bf16 v[92:95], v[226:229], v[16:19], v[214:217]
	s_cbranch_vccz .LBB0_1058
	v_sub_f32_e32 v2, v2, v123
	v_exp_f32_e32 v2, v2
	s_nop 0
	v_pk_mul_f32 v[74:75], v[74:75], v[2:3] op_sel_hi:[1,0]
	v_pk_mul_f32 v[72:73], v[72:73], v[2:3] op_sel_hi:[1,0]
	v_pk_mul_f32 v[70:71], v[70:71], v[2:3] op_sel_hi:[1,0]
	v_pk_mul_f32 v[68:69], v[68:69], v[2:3] op_sel_hi:[1,0]
	v_pk_mul_f32 v[66:67], v[66:67], v[2:3] op_sel_hi:[1,0]
	v_pk_mul_f32 v[64:65], v[64:65], v[2:3] op_sel_hi:[1,0]
	v_pk_mul_f32 v[58:59], v[58:59], v[2:3] op_sel_hi:[1,0]
	v_pk_mul_f32 v[56:57], v[56:57], v[2:3] op_sel_hi:[1,0]
	v_pk_mul_f32 v[62:63], v[62:63], v[2:3] op_sel_hi:[1,0]
	v_pk_mul_f32 v[60:61], v[60:61], v[2:3] op_sel_hi:[1,0]
.LBB0_1058:
	v_add_f32_e32 v88, v104, v88
	v_add_f32_e32 v89, v105, v89
	v_add_f32_e32 v90, v106, v90
	v_add_f32_e32 v91, v107, v91
	v_max3_f32 v2, v88, s94, v89
	v_add_f32_e32 v84, v100, v84
	v_add_f32_e32 v85, v101, v85
	v_max3_f32 v2, v2, v90, v91
	v_add_f32_e32 v86, v102, v86
	v_add_f32_e32 v87, v103, v87
	v_max3_f32 v2, v2, v84, v85
	v_add_f32_e32 v80, v96, v80
	v_add_f32_e32 v81, v97, v81
	v_max3_f32 v2, v2, v86, v87
	v_add_f32_e32 v82, v98, v82
	v_add_f32_e32 v83, v99, v83
	v_max3_f32 v2, v2, v80, v81
	v_add_f32_e32 v76, v92, v76
	v_add_f32_e32 v77, v93, v77
	v_max3_f32 v2, v2, v82, v83
	v_add_f32_e32 v78, v94, v78
	v_add_f32_e32 v79, v95, v79
	v_max3_f32 v2, v2, v76, v77
	v_max3_f32 v2, v2, v78, v79
	v_mov_b32_e32 v92, v2
	s_nop 1
	v_permlane16_swap_b32 v92, v2
	s_waitcnt lgkmcnt(0)
	v_max_f32_e32 v2, v2, v92
	v_mov_b32_e32 v92, v2
	s_nop 1
	v_permlane32_swap_b32 v92, v2
	s_waitcnt lgkmcnt(0)
	v_max3_f32 v109, v3, v2, v92
	v_cmp_neq_f32_e32 vcc, s94, v109
	s_nop 1
	v_cndmask_b32_e32 v2, 0, v109, vcc
	v_cmp_gt_f32_e32 vcc, v109, v3
	s_cbranch_vccz .LBB0_1060
	v_sub_f32_e32 v3, v3, v2
	v_exp_f32_e32 v92, v3
	s_nop 0
	v_pk_mul_f32 v[42:43], v[42:43], v[92:93] op_sel_hi:[1,0]
	v_pk_mul_f32 v[40:41], v[40:41], v[92:93] op_sel_hi:[1,0]
	v_pk_mul_f32 v[54:55], v[54:55], v[92:93] op_sel_hi:[1,0]
	v_pk_mul_f32 v[52:53], v[52:53], v[92:93] op_sel_hi:[1,0]
	v_pk_mul_f32 v[50:51], v[50:51], v[92:93] op_sel_hi:[1,0]
	v_pk_mul_f32 v[48:49], v[48:49], v[92:93] op_sel_hi:[1,0]
	v_pk_mul_f32 v[46:47], v[46:47], v[92:93] op_sel_hi:[1,0]
	v_pk_mul_f32 v[44:45], v[44:45], v[92:93] op_sel_hi:[1,0]
	v_pk_mul_f32 v[38:39], v[38:39], v[92:93] op_sel_hi:[1,0]
	v_pk_mul_f32 v[36:37], v[36:37], v[92:93] op_sel_hi:[1,0]
